# k58: k57 + layer-1 prompt-chain workgroups run two sample units each (896+c, 960+c) before their chain
# speedup vs baseline: 1.0002x; 1.0002x over previous
; #define LAS __attribute__((address_space(3)))
; __device__ __forceinline__ void mix_hg_unit(Frame& F, int b, int h, int mode) {
;     const bool prompt = (mode != 1);
;     const int tid = F.tid, lane = F.lane, w = F.wave, r16 = lane & 15, q = lane >> 4;
;     const int tk = tid >> 3, p = tid & 7;
;     LAS unsigned char* L = F.lds;
;     LAS float* GD = (LAS float*)(L + MX_GD); LAS float* OB = (LAS float*)(L + MX_OB);
;     bf16* MIX = F_XN(F);
;     f32x4 S[8];
; #pragma unroll
;     for (int mt = 0; mt < 8; ++mt) S[mt] = (f32x4){0.f, 0.f, 0.f, 0.f};
;     if (!prompt) {
;         const float* Sin = F.in[6] + (size_t)(b * 8 + h) * 16384;
; #pragma unroll
;         for (int mt = 0; mt < 8; ++mt)
; #pragma unroll
;             for (int r = 0; r < 4; ++r) S[mt][r] = __builtin_nontemporal_load(Sin + (16 * mt + 4 * q + r) * 128 + 16 * w + r16);
;     }
;     LAS float* GN = (LAS float*)(L + MX_GN);
;     if (tid < 128) GN[tid] = F.in[18][128 * h + tid];
;     const int nsc = (mode == 0) ? 33 : 1;
;     u32x4 pa[6]; u32x4 pg[2]; float pgd = 1.f;
;     ...
;     const int zvo = tk * 8192 + (128 * h + 16 * p) * 2;
;     HG_LOAD(0);
; __device__ __forceinline__ void mixer_layer1(Frame& F) {
;     int bid = blockIdx.x; asm volatile("" : "+s"(bid));
;     if (bid < 64) { mix_hg_unit(F, bid >> 3, bid & 7, 0); return; }
; #pragma unroll 1
;     for (int u = bid - 64; u < 1024 + 8; u += F.G - 64) {
;         if (u < 1024) mix_hg_unit(F, u >> 3, u & 7, 1); else mix_hg_unit(F, 0, u - 1024, 2);
;     }
.LBB0_847:
	s_andn2_b64 vcc, exec, s[0:1]
	s_cbranch_vccnz .LBB0_898
	s_mov_b32 s0, s42
	s_mov_b64 s[4:5], -1
	s_cmpk_gt_u32 s0, 0x447
	s_cbranch_scc1 .LBB0_874
	s_waitcnt vmcnt(0) lgkmcnt(0)
	v_ashrrev_i32_e32 v4, 7, v145
	v_ashrrev_i32_e32 v5, 31, v4
	v_readlane_b32 s10, v253, 19
	s_movk_i32 s1, 0x80
	v_cmp_gt_i32_e64 s[8:9], 1, v4
	v_lshlrev_b64 v[4:5], 12, v[4:5]
	v_and_b32_e32 v6, 0x7f, v145
	v_readlane_b32 s11, v253, 20
	v_and_b32_e32 v1, 7, v145
	v_cmp_gt_i32_e64 s[4:5], s1, v145
	s_movk_i32 s1, 0x7f
	v_lshlrev_b32_e32 v9, 2, v145
	v_lshl_add_u64 v[4:5], s[10:11], 0, v[4:5]
	v_lshlrev_b32_e32 v2, 2, v6
	v_cmp_lt_i32_e64 s[6:7], s1, v145
	v_lshlrev_b32_e32 v106, 4, v1
	v_lshl_add_u64 v[4:5], v[4:5], 0, v[2:3]
	v_and_b32_e32 v2, 4, v9
	s_movk_i32 s1, 0x60
	v_ashrrev_i32_e32 v0, 3, v145
	v_and_or_b32 v2, v106, s1, v2
	s_movk_i32 s12, 0x110
	v_lshlrev_b32_e32 v107, 1, v2
	v_mul_lo_u32 v2, v0, s12
	s_movk_i32 s15, 0x210
	v_lshrrev_b32_e32 v8, 4, v190
	v_readlane_b32 s13, v253, 62
	v_add_u32_e32 v108, 0, v2
	v_lshlrev_b32_e32 v94, 5, v1
	v_mul_lo_u32 v2, v0, s15
	v_lshlrev_b32_e32 v1, 6, v1
	v_readlane_b32 s14, v253, 63
	s_mov_b64 s[10:11], 0x440000
	v_readlane_b32 s25, v254, 7
	v_add3_u32 v110, s14, v2, v1
	v_add_u32_e32 v111, s13, v1
	v_lshlrev_b32_e32 v1, 2, v8
	v_add_u32_e32 v104, s13, v9
	v_lshl_add_u64 v[92:93], v[4:5], 0, s[10:11]
	v_add_u32_e32 v109, s25, v9
	v_or_b32_e32 v4, 3, v1
	v_mov_b32_e32 v9, 0xfffffdf0
	v_and_b32_e32 v7, 15, v145
	v_readlane_b32 s10, v252, 57
	s_and_b32 s1, s47, 0xffffffc0
	v_mad_u32_u24 v115, v4, s15, v9
	v_bfe_u32 v9, v145, 2, 2
	v_mov_b32_e32 v95, v3
	v_readlane_b32 s11, v252, 58
	s_add_i32 s1, s1, s14
	v_or_b32_e32 v5, 2, v1
	v_or_b32_e32 v9, v1, v9
	v_cmp_lt_u32_e64 s[14:15], v1, v7
	v_cmp_gt_u32_e64 s[16:17], v1, v7
	v_ashrrev_i32_e32 v1, 31, v0
	v_lshl_add_u64 v[96:97], s[10:11], 0, v[94:95]
	v_mad_u32_u24 v95, v7, s12, 0
	v_mul_u32_u24_e32 v114, 0x210, v4
	v_mad_u32_u24 v9, v9, s12, 0
	v_cmp_gt_u32_e64 s[10:11], v4, v7
	v_cmp_gt_u32_e64 s[12:13], v5, v7
	v_lshlrev_b64 v[4:5], 11, v[0:1]
	v_lshl_add_u64 v[4:5], v[96:97], 0, v[4:5]
	s_mov_b64 s[22:23], 0x2200000
	v_lshl_add_u64 v[98:99], v[4:5], 0, s[22:23]
	s_lshl_b32 s22, s46, 4
	s_ashr_i32 s23, s22, 31
	s_mov_b32 s43, s71
	v_readlane_b32 s56, v251, 5
	s_sub_i32 s24, s0, 64
	s_mov_b32 s100, s87
	s_movk_i32 s101, 0x3ff
	s_cmp_gt_i32 s0, 63
	s_cbranch_scc1 .Lmx1_side
	s_add_i32 s24, s0, 0x380
	s_movk_i32 s100, 64
	s_movk_i32 s101, 0x407
.Lmx1_side:
	s_lshl_b64 s[26:27], s[22:23], 2
	v_readlane_b32 s68, v251, 17
	v_readlane_b32 s69, v251, 18
	s_add_u32 s22, s68, s26
	v_lshlrev_b32_e32 v2, 2, v7
	s_addc_u32 s23, s69, s27
	v_lshlrev_b32_e32 v105, 13, v0
	v_add_u32_e32 v113, s1, v2
	v_lshlrev_b32_e32 v10, 3, v145
	v_lshl_add_u64 v[4:5], s[22:23], 0, v[2:3]
	v_and_b32_e32 v1, 48, v190
	v_cmp_gt_i32_e64 s[22:23], 8, v0
	v_readlane_b32 s1, v253, 23
	v_and_b32_e32 v118, 24, v10
	v_cmp_gt_i32_e64 s[18:19], 16, v0
	v_cmp_lt_i32_e64 s[20:21], 15, v0
	v_readlane_b32 s62, v251, 11
	v_readlane_b32 s63, v251, 12
	v_readlane_b32 s64, v251, 13
	v_readlane_b32 s65, v251, 14
	v_add_u32_e32 v119, s25, v1
	v_lshlrev_b32_e32 v2, 4, v7
	v_cndmask_b32_e64 v120, 0, v0, s[22:23]
	s_add_u32 s1, s1, s26
	v_readlane_b32 s25, v253, 24
	v_lshl_add_u32 v0, s0, 8, v105
	v_readlane_b32 s66, v251, 15
	v_readlane_b32 s67, v251, 16
	v_readlane_b32 s71, v251, 20
	v_readlane_b32 s64, v252, 3
	v_readlane_b32 s62, v253, 29
	v_lshlrev_b32_e32 v1, 1, v118
	v_or_b32_e32 v7, 0xc0, v2
	v_or_b32_e32 v10, 0xc8, v2
	s_addc_u32 s38, s25, s27
	v_lshlrev_b32_e32 v2, 11, v8
	s_lshl_b32 s25, s0, 7
	v_or_b32_e32 v0, v0, v94
	v_and_b32_e32 v112, 48, v145
	v_mul_u32_u24_e32 v116, 0x840, v8
	v_lshl_add_u32 v117, s46, 5, v9
	v_readlane_b32 s65, v252, 4
	v_readlane_b32 s66, v254, 30
	s_mov_b32 s71, s43
	v_readlane_b32 s63, v253, 30
	v_lshl_add_u64 v[100:101], v[4:5], 0, v[2:3]
	s_add_i32 s26, s25, 0xfffde000
	s_cmp_gt_i32 s0, 63
	s_cbranch_scc1 .Lmx1_side2
	s_add_i32 s26, s25, 0xffffc000
.Lmx1_side2:
	v_add_u32_e32 v121, 0xfffbc000, v0
	s_cmp_gt_i32 s0, 63
	s_cbranch_scc1 .Lmx1_side3
	v_add_u32_e32 v121, 0xffff8000, v0

; __device__ __forceinline__ void mixer_layer1(Frame& F) {
;     ...
; #pragma unroll 1
;     for (int u = bid - 64; u < 1024 + 8; u += F.G - 64) {
;         if (u < 1024) mix_hg_unit(F, u >> 3, u & 7, 1); else mix_hg_unit(F, 0, u - 1024, 2);
.LBB0_853:
	s_cmp_lt_i32 s0, 64
	s_cbranch_scc1 .Lmx1_go
	s_cmpk_lt_i32 s24, 0x380
	s_cbranch_scc1 .Lmx1_go
	s_cmpk_gt_i32 s24, 0x3ff
	s_cbranch_scc0 .LBB0_852
